# gdn_intra q/k l2-norm 16-lane reductions via DPP quad_perm/row_half_mirror/row_mirror adds instead of ds_bpermute round trips (bit-identical sums)
# speedup vs baseline: 1.0043x; 1.0043x over previous
; #define LAS __attribute__((address_space(3)))
; DI unsigned pk2(float lo, float hi) { f32x2 v = {lo, hi}; bf2_t b = __builtin_convertvector(v, bf2_t); return __builtin_bit_cast(unsigned, b); }
; DI void unpack8(u32x4 w, float* f) { f[0] = bflo(w.x); f[1] = bfhi(w.x); f[2] = bflo(w.y); f[3] = bfhi(w.y); f[4] = bflo(w.z); f[5] = bfhi(w.z); f[6] = bflo(w.w); f[7] = bfhi(w.w); }
; DI u32x4 pack8(const float* f) { u32x4 w; w.x = pk2(f[0], f[1]); w.y = pk2(f[2], f[3]); w.z = pk2(f[4], f[5]); w.w = pk2(f[6], f[7]); return w; }
; DI void gdn_intra(LAS unsigned char* lds, PP p, int l, int first, int stride) {
;     ...
;             float a[8];
; #pragma unroll
;             for (int i = 0; i < 8; ++i) a[i] = 0.f;
; #pragma unroll
;             for (int kk = 0; kk < 4; ++kk) { const bool ok = tok0 + j - 3 + kk >= 0;
;                 float x[8]; unpack8(R[(mat * 2 + it) * 4 + kk], x);
;                 const f32x4 w0 = *(const LAS f32x4*)(CW + kk * 384 + mat * 128 + o * 8), w1 = *(const LAS f32x4*)(CW + kk * 384 + mat * 128 + o * 8 + 4);
;                 for (int i = 0; i < 4; ++i) { a[i] += ok ? w0[i] * x[i] : 0.f; a[4 + i] += ok ? w1[i] * x[4 + i] : 0.f; } }
; #pragma unroll
;             for (int i = 0; i < 8; ++i) a[i] = a[i] / (1.f + __expf(-a[i]));
;             if (mat < 2) {
;                 float ss = 0.f;
; #pragma unroll
;                 for (int i = 0; i < 8; ++i) ss += a[i] * a[i];
;                 ss += __shfl_xor(ss, 1); ss += __shfl_xor(ss, 2); ss += __shfl_xor(ss, 4); ss += __shfl_xor(ss, 8);
;                 const float sc = rsqrtf(ss + 1e-6f) * (mat == 0 ? 0.08838834764831845f : 1.f);
; #pragma unroll
;                 for (int i = 0; i < 8; ++i) a[i] *= sc;
;             }
;             if (mat == 0) {
;                 *(LAS u32x4*)(Qn + j * 136 + o * 8) = pack8(a);
;                 const float eg = sce[j]; const int ct = j >> 5, s = o >> 1, part = o & 1;
;                 unsigned char* q0 = fb + 16384 + ((size_t)((ct * 8 + s) * 64 + (j & 31))) * 16 + 8 * part;
;                 u32x2 lo, hi2; lo.x = pk2(a[0] * eg, a[1] * eg); lo.y = pk2(a[2] * eg, a[3] * eg); hi2.x = pk2(a[4] * eg, a[5] * eg); hi2.y = pk2(a[6] * eg, a[7] * eg);
;                 *(u32x2*)q0 = lo; *(u32x2*)(q0 + 32 * 16) = hi2;
.LBB0_484:
	s_or_b64 exec, exec, s[2:3]
	s_mul_i32 s3, s54, 0xe000
	s_mul_hi_i32 s2, s54, 0xe000
	s_add_u32 s58, s56, s3
	v_lshlrev_b32_e32 v25, 3, v138
	s_addc_u32 s59, s60, s2
	v_and_b32_e32 v2, 8, v25
	s_waitcnt lgkmcnt(1)
	v_lshl_add_u64 v[12:13], s[58:59], 0, v[2:3]
	v_add_f32_e32 v2, v0, v11
	v_mul_f32_e32 v0, 0xbfb8aa3b, v2
	s_waitcnt lgkmcnt(0)
	v_and_b32_e32 v18, 64, v220
	s_mov_b64 s[2:3], 0x4000
	v_exp_f32_e32 v1, v0
	v_mul_f32_e32 v0, 0xbfb8aa3b, v4
	v_xor_b32_e32 v11, 1, v220
	v_add_u32_e32 v18, 64, v18
	v_and_b32_e32 v143, 0x1c0, v20
	v_lshl_add_u64 v[20:21], v[12:13], 0, s[2:3]
	v_exp_f32_e32 v12, v0
	v_mul_f32_e32 v0, 0xbfb8aa3b, v5
	v_cmp_lt_i32_e32 vcc, v11, v18
	v_exp_f32_e32 v13, v0
	v_mul_f32_e32 v0, 0xbfb8aa3b, v6
	v_cndmask_b32_e32 v11, v220, v11, vcc
	v_exp_f32_e32 v14, v0
	v_mul_f32_e32 v0, 0xbfb8aa3b, v7
	v_lshlrev_b32_e32 v31, 2, v11
	v_xor_b32_e32 v11, 2, v220
	v_exp_f32_e32 v15, v0
	v_mul_f32_e32 v0, 0xbfb8aa3b, v8
	v_cmp_lt_i32_e32 vcc, v11, v18
	v_exp_f32_e32 v16, v0
	v_mul_f32_e32 v0, 0xbfb8aa3b, v9
	v_cndmask_b32_e32 v11, v220, v11, vcc
	v_exp_f32_e32 v17, v0
	v_mul_f32_e32 v0, 0xbfb8aa3b, v10
	v_lshlrev_b32_e32 v32, 2, v11
	v_xor_b32_e32 v11, 4, v220
	v_exp_f32_e32 v0, v0
	v_cmp_lt_i32_e32 vcc, v11, v18
	v_pk_add_f32 v[16:17], v[16:17], 1.0 op_sel_hi:[1,0]
	v_pk_add_f32 v[14:15], v[14:15], 1.0 op_sel_hi:[1,0]
	v_cndmask_b32_e32 v11, v220, v11, vcc
	v_lshlrev_b32_e32 v33, 2, v11
	v_xor_b32_e32 v11, 8, v220
	v_cmp_lt_i32_e32 vcc, v11, v18
	v_pk_add_f32 v[0:1], v[0:1], 1.0 op_sel_hi:[1,0]
	v_pk_add_f32 v[12:13], v[12:13], 1.0 op_sel_hi:[1,0]
	v_cndmask_b32_e32 v11, v220, v11, vcc
	v_lshlrev_b32_e32 v34, 2, v11
	v_rcp_f32_e32 v18, v1
	s_nop 0
	v_lshl_add_u32 v141, v28, 4, v132
	v_lshl_add_u32 v139, v24, 2, v35
	v_mul_f32_e32 v27, v2, v18
	v_fma_f32 v29, -v1, v27, v2
	v_fmac_f32_e32 v27, v29, v18
	v_div_fixup_f32 v1, v27, v1, v2
	v_rcp_f32_e32 v11, v0
	s_nop 0
	v_mul_f32_e32 v19, v10, v11
	v_fma_f32 v27, -v0, v19, v10
	v_fmac_f32_e32 v19, v27, v11
	v_div_fixup_f32 v0, v19, v0, v10
	v_rcp_f32_e32 v18, v17
	s_nop 0
	v_pk_mul_f32 v[10:11], v[0:1], v[0:1]
	v_mul_f32_e32 v27, v9, v18
	v_fma_f32 v29, -v17, v27, v9
	v_fmac_f32_e32 v27, v29, v18
	v_div_fixup_f32 v9, v27, v17, v9
	v_rcp_f32_e32 v17, v16
	s_nop 0
	v_mul_f32_e32 v19, v8, v17
	v_fma_f32 v27, -v16, v19, v8
	v_fmac_f32_e32 v19, v27, v17
	v_div_fixup_f32 v8, v19, v16, v8
	v_rcp_f32_e32 v18, v15
	s_nop 0
	v_pk_mul_f32 v[16:17], v[8:9], v[8:9]
	v_mul_f32_e32 v27, v7, v18
	v_fma_f32 v29, -v15, v27, v7
	v_fmac_f32_e32 v27, v29, v18
	v_div_fixup_f32 v7, v27, v15, v7
	v_rcp_f32_e32 v15, v14
	s_nop 0
	v_mul_f32_e32 v19, v6, v15
	v_fma_f32 v27, -v14, v19, v6
	v_fmac_f32_e32 v19, v27, v15
	v_div_fixup_f32 v6, v19, v14, v6
	v_rcp_f32_e32 v18, v13
	s_nop 0
	v_pk_mul_f32 v[14:15], v[6:7], v[6:7]
	v_mul_f32_e32 v27, v5, v18
	v_fma_f32 v29, -v13, v27, v5
	v_fmac_f32_e32 v27, v29, v18
	v_div_fixup_f32 v5, v27, v13, v5
	v_rcp_f32_e32 v13, v12
	s_nop 0
	s_movk_i32 s2, 0x110
	v_mul_f32_e32 v19, v4, v13
	v_fma_f32 v27, -v12, v19, v4
	v_fmac_f32_e32 v19, v27, v13
	v_div_fixup_f32 v4, v19, v12, v4
	v_pk_mul_f32 v[12:13], v[4:5], v[4:5]
	s_nop 0
	v_add_f32_e32 v2, v12, v13
	v_add_f32_e32 v2, v14, v2
	v_add_f32_e32 v2, v15, v2
	v_add_f32_e32 v2, v16, v2
	v_add_f32_e32 v2, v17, v2
	v_add_f32_e32 v2, v10, v2
	v_add_f32_e32 v2, v11, v2
	s_waitcnt lgkmcnt(0)
	s_nop 1
	v_add_f32_dpp v2, v2, v2 quad_perm:[1,0,3,2] row_mask:0xf bank_mask:0xf
	s_nop 1
	v_add_f32_dpp v2, v2, v2 quad_perm:[2,3,0,1] row_mask:0xf bank_mask:0xf
	s_nop 1
	v_add_f32_dpp v2, v2, v2 row_half_mirror row_mask:0xf bank_mask:0xf
	s_nop 1
	v_add_f32_dpp v2, v2, v2 row_mirror row_mask:0xf bank_mask:0xf
	v_add_f32_e32 v2, 0x358637bd, v2
	v_cmp_gt_f32_e32 vcc, s10, v2
	v_mul_f32_e32 v10, 0x4b800000, v2
	s_nop 0
	v_cndmask_b32_e32 v2, v2, v10, vcc
	v_rsq_f32_e32 v2, v2
	s_nop 0
	v_mul_f32_e32 v10, 0x45800000, v2
	v_cndmask_b32_e32 v2, v2, v10, vcc
	v_mul_f32_e32 v2, 0x3db504f3, v2
	v_pk_mul_f32 v[10:11], v[4:5], v[2:3] op_sel_hi:[1,0]
	v_pk_mul_f32 v[12:13], v[6:7], v[2:3] op_sel_hi:[1,0]
	v_pk_mul_f32 v[8:9], v[8:9], v[2:3] op_sel_hi:[1,0]
	v_pk_mul_f32 v[0:1], v[0:1], v[2:3] op_sel_hi:[1,0]
	v_mul_lo_u32 v2, v24, s2
	v_cvt_pk_bf16_f32 v4, v10, v11
	v_cvt_pk_bf16_f32 v5, v12, v13
	v_cvt_pk_bf16_f32 v6, v8, v9
	v_cvt_pk_bf16_f32 v7, v0, v1
	v_add_u32_e32 v140, v141, v2
	ds_write_b128 v140, v[4:7]
	ds_read_b32 v2, v139
	v_and_b32_e32 v4, 0xfffffe00, v138
	v_bfe_u32 v5, v138, 4, 5
	v_or3_b32 v4, v5, v4, v143
	v_ashrrev_i32_e32 v5, 31, v4
	s_waitcnt lgkmcnt(0)
	v_pk_mul_f32 v[6:7], v[2:3], v[10:11] op_sel_hi:[0,1]
	v_pk_mul_f32 v[10:11], v[2:3], v[12:13] op_sel_hi:[0,1]
	v_pk_mul_f32 v[8:9], v[2:3], v[8:9] op_sel_hi:[0,1]
	v_lshl_add_u64 v[4:5], v[4:5], 4, v[20:21]
	v_cvt_pk_bf16_f32 v6, v6, v7
	v_cvt_pk_bf16_f32 v7, v10, v11
	v_cvt_pk_bf16_f32 v8, v8, v9
	v_pk_mul_f32 v[0:1], v[2:3], v[0:1] op_sel_hi:[0,1]
	v_cvt_pk_bf16_f32 v9, v0, v1
	global_store_dwordx2 v[4:5], v[6:7], off
	global_store_dwordx2 v[4:5], v[8:9], off offset:512
	ds_read_b128 v[12:15], v26
	ds_read_b128 v[16:19], v26 offset:16
	v_add_u32_e32 v29, 0x200, v138
	v_ashrrev_i32_e32 v27, 4, v29
	v_add_u32_e32 v142, s20, v27
	v_lshlrev_b32_e32 v0, 16, v62
	v_lshlrev_b32_e32 v4, 16, v60
	v_and_b32_e32 v2, 0xffff0000, v62
	s_waitcnt lgkmcnt(1)
	v_fma_f32 v4, v12, v4, 0
	s_waitcnt lgkmcnt(0)
	v_mul_f32_e32 v5, v16, v0
	v_cmp_lt_i32_e64 s[44:45], 2, v142
	v_and_b32_e32 v1, 0xffff0000, v60
	v_fma_f32 v1, v13, v1, 0
	v_cndmask_b32_e64 v0, 0, v4, s[44:45]
	v_cndmask_b32_e64 v4, 0, v5, s[44:45]
	v_mul_f32_e32 v5, v17, v2
	v_cndmask_b32_e64 v5, 0, v5, s[44:45]
	v_cmp_gt_i32_e64 s[42:43], 3, v142
	v_add_f32_e32 v4, 0, v4
	v_cndmask_b32_e64 v1, 0, v1, s[44:45]
	v_mov_b32_e32 v2, v3
	v_mov_b32_e32 v6, v3
	v_mov_b32_e32 v7, v3
	v_add_f32_e32 v5, 0, v5
	s_and_saveexec_b64 s[2:3], s[42:43]
	s_xor_b64 s[2:3], exec, s[2:3]
	s_or_saveexec_b64 s[2:3], s[2:3]
	v_mov_b32_e32 v8, 0
	s_xor_b64 exec, exec, s[2:3]
	v_lshlrev_b32_e32 v8, 16, v63
	v_lshlrev_b32_e32 v2, 16, v61
	v_fma_f32 v2, v14, v2, 0
	v_mul_f32_e32 v8, v18, v8
	s_or_b64 exec, exec, s[2:3]
	v_add_f32_e32 v12, v6, v8
	v_mov_b64_e32 v[10:11], v[6:7]
	v_mov_b64_e32 v[8:9], v[4:5]
	v_mov_b64_e32 v[6:7], v[2:3]
	v_mov_b64_e32 v[4:5], v[0:1]
	v_mov_b32_e32 v10, v12
	s_and_saveexec_b64 s[2:3], s[42:43]
	s_xor_b64 s[2:3], exec, s[2:3]
	v_add_f32_e32 v7, 0, v3
	s_or_saveexec_b64 s[2:3], s[2:3]
	v_mov_b32_e32 v0, 0
	s_xor_b64 exec, exec, s[2:3]
	v_and_b32_e32 v0, 0xffff0000, v61
	v_and_b32_e32 v1, 0xffff0000, v63
	v_mov_b32_e32 v7, v3
	v_fmac_f32_e32 v7, v15, v0
	v_mul_f32_e32 v0, v19, v1
	s_or_b64 exec, exec, s[2:3]
	ds_read_b128 v[12:15], v26 offset:1536
	ds_read_b128 v[16:19], v26 offset:1552
	v_add_f32_e32 v11, v11, v0
	v_cmp_gt_i32_e64 s[34:35], 2, v142
	s_and_saveexec_b64 s[2:3], s[34:35]
	s_xor_b64 s[2:3], exec, s[2:3]
	v_add_f32_e32 v4, 0, v4
	s_or_saveexec_b64 s[2:3], s[2:3]
	v_mov_b32_e32 v0, 0
	s_xor_b64 exec, exec, s[2:3]
	s_cbranch_execz .LBB0_494
; #define LAS __attribute__((address_space(3)))
; DI void unpack8(u32x4 w, float* f) { f[0] = bflo(w.x); f[1] = bfhi(w.x); f[2] = bflo(w.y); f[3] = bfhi(w.y); f[4] = bflo(w.z); f[5] = bfhi(w.z); f[6] = bflo(w.w); f[7] = bfhi(w.w); }
; DI void gdn_intra(LAS unsigned char* lds, PP p, int l, int first, int stride) {
;     ...
;             for (int kk = 0; kk < 4; ++kk) { const bool ok = tok0 + j - 3 + kk >= 0;
;                 float x[8]; unpack8(R[(mat * 2 + it) * 4 + kk], x);
;                 const f32x4 w0 = *(const LAS f32x4*)(CW + kk * 384 + mat * 128 + o * 8), w1 = *(const LAS f32x4*)(CW + kk * 384 + mat * 128 + o * 8 + 4);
;                 for (int i = 0; i < 4; ++i) { a[i] += ok ? w0[i] * x[i] : 0.f; a[4 + i] += ok ? w1[i] * x[4 + i] : 0.f; } }
	v_lshlrev_b32_e32 v0, 16, v74
	v_lshlrev_b32_e32 v1, 16, v72
	s_waitcnt lgkmcnt(1)
	v_fmac_f32_e32 v4, v12, v1
	s_waitcnt lgkmcnt(0)
	v_mul_f32_e32 v0, v16, v0

; #define LAS __attribute__((address_space(3)))
; DI unsigned pk2(float lo, float hi) { f32x2 v = {lo, hi}; bf2_t b = __builtin_convertvector(v, bf2_t); return __builtin_bit_cast(unsigned, b); }
; DI void unpack8(u32x4 w, float* f) { f[0] = bflo(w.x); f[1] = bfhi(w.x); f[2] = bflo(w.y); f[3] = bfhi(w.y); f[4] = bflo(w.z); f[5] = bfhi(w.z); f[6] = bflo(w.w); f[7] = bfhi(w.w); }
; DI u32x4 pack8(const float* f) { u32x4 w; w.x = pk2(f[0], f[1]); w.y = pk2(f[2], f[3]); w.z = pk2(f[4], f[5]); w.w = pk2(f[6], f[7]); return w; }
; DI void gdn_intra(LAS unsigned char* lds, PP p, int l, int first, int stride) {
;     ...
;             for (int kk = 0; kk < 4; ++kk) { const bool ok = tok0 + j - 3 + kk >= 0;
;                 float x[8]; unpack8(R[(mat * 2 + it) * 4 + kk], x);
;                 const f32x4 w0 = *(const LAS f32x4*)(CW + kk * 384 + mat * 128 + o * 8), w1 = *(const LAS f32x4*)(CW + kk * 384 + mat * 128 + o * 8 + 4);
;                 for (int i = 0; i < 4; ++i) { a[i] += ok ? w0[i] * x[i] : 0.f; a[4 + i] += ok ? w1[i] * x[4 + i] : 0.f; } }
; #pragma unroll
;             for (int i = 0; i < 8; ++i) a[i] = a[i] / (1.f + __expf(-a[i]));
;             if (mat < 2) {
;                 float ss = 0.f;
; #pragma unroll
;                 for (int i = 0; i < 8; ++i) ss += a[i] * a[i];
;                 ss += __shfl_xor(ss, 1); ss += __shfl_xor(ss, 2); ss += __shfl_xor(ss, 4); ss += __shfl_xor(ss, 8);
;                 const float sc = rsqrtf(ss + 1e-6f) * (mat == 0 ? 0.08838834764831845f : 1.f);
; #pragma unroll
;                 for (int i = 0; i < 8; ++i) a[i] *= sc;
;             }
;             if (mat == 0) {
;                 *(LAS u32x4*)(Qn + j * 136 + o * 8) = pack8(a);
;                 const float eg = sce[j]; const int ct = j >> 5, s = o >> 1, part = o & 1;
;                 unsigned char* q0 = fb + 16384 + ((size_t)((ct * 8 + s) * 64 + (j & 31))) * 16 + 8 * part;
;                 u32x2 lo, hi2; lo.x = pk2(a[0] * eg, a[1] * eg); lo.y = pk2(a[2] * eg, a[3] * eg); hi2.x = pk2(a[4] * eg, a[5] * eg); hi2.y = pk2(a[6] * eg, a[7] * eg);
;                 *(u32x2*)q0 = lo; *(u32x2*)(q0 + 32 * 16) = hi2;
.LBB0_538:
	s_or_b64 exec, exec, s[2:3]
	v_add_f32_e32 v2, v0, v11
	v_mul_f32_e32 v0, 0xbfb8aa3b, v2
	v_exp_f32_e32 v1, v0
	v_mul_f32_e32 v0, 0xbfb8aa3b, v4
	s_waitcnt lgkmcnt(1)
	v_exp_f32_e32 v12, v0
	v_mul_f32_e32 v0, 0xbfb8aa3b, v5
	v_exp_f32_e32 v13, v0
	v_mul_f32_e32 v0, 0xbfb8aa3b, v6
	v_exp_f32_e32 v14, v0
	v_mul_f32_e32 v0, 0xbfb8aa3b, v7
	v_exp_f32_e32 v15, v0
	v_mul_f32_e32 v0, 0xbfb8aa3b, v8
	s_waitcnt lgkmcnt(0)
	v_exp_f32_e32 v16, v0
	v_mul_f32_e32 v0, 0xbfb8aa3b, v9
	v_exp_f32_e32 v17, v0
	v_mul_f32_e32 v0, 0xbfb8aa3b, v10
	v_exp_f32_e32 v0, v0
	v_pk_add_f32 v[14:15], v[14:15], 1.0 op_sel_hi:[1,0]
	v_pk_add_f32 v[16:17], v[16:17], 1.0 op_sel_hi:[1,0]
	v_pk_add_f32 v[12:13], v[12:13], 1.0 op_sel_hi:[1,0]
	v_pk_add_f32 v[0:1], v[0:1], 1.0 op_sel_hi:[1,0]
	s_nop 0
	v_rcp_f32_e32 v18, v1
	s_nop 0
	v_mul_f32_e32 v142, v2, v18
	v_fma_f32 v144, -v1, v142, v2
	v_fmac_f32_e32 v142, v144, v18
	v_div_fixup_f32 v1, v142, v1, v2
	v_rcp_f32_e32 v11, v0
	s_nop 0
	v_mul_f32_e32 v19, v10, v11
	v_fma_f32 v142, -v0, v19, v10
	v_fmac_f32_e32 v19, v142, v11
	v_div_fixup_f32 v0, v19, v0, v10
	v_rcp_f32_e32 v18, v17
	s_nop 0
	v_pk_mul_f32 v[10:11], v[0:1], v[0:1]
	v_mul_f32_e32 v142, v9, v18
	v_fma_f32 v144, -v17, v142, v9
	v_fmac_f32_e32 v142, v144, v18
	v_div_fixup_f32 v9, v142, v17, v9
	v_rcp_f32_e32 v17, v16
	s_nop 0
	v_mul_f32_e32 v19, v8, v17
	v_fma_f32 v142, -v16, v19, v8
	v_fmac_f32_e32 v19, v142, v17
	v_div_fixup_f32 v8, v19, v16, v8
	v_rcp_f32_e32 v18, v15
	s_nop 0
	v_pk_mul_f32 v[16:17], v[8:9], v[8:9]
	v_mul_f32_e32 v142, v7, v18
	v_fma_f32 v144, -v15, v142, v7
	v_fmac_f32_e32 v142, v144, v18
	v_div_fixup_f32 v7, v142, v15, v7
	v_rcp_f32_e32 v15, v14
	s_nop 0
	v_mul_f32_e32 v19, v6, v15
	v_fma_f32 v142, -v14, v19, v6
	v_fmac_f32_e32 v19, v142, v15
	v_div_fixup_f32 v6, v19, v14, v6
	v_rcp_f32_e32 v18, v13
	s_nop 0
	v_pk_mul_f32 v[14:15], v[6:7], v[6:7]
	v_mul_f32_e32 v142, v5, v18
	v_fma_f32 v144, -v13, v142, v5
	v_fmac_f32_e32 v142, v144, v18
	v_div_fixup_f32 v5, v142, v13, v5
	v_rcp_f32_e32 v13, v12
	s_nop 0
	s_movk_i32 s2, 0x110
	v_mul_f32_e32 v19, v4, v13
	v_fma_f32 v142, -v12, v19, v4
	v_fmac_f32_e32 v19, v142, v13
	v_div_fixup_f32 v4, v19, v12, v4
	v_pk_mul_f32 v[12:13], v[4:5], v[4:5]
	s_nop 0
	v_add_f32_e32 v2, v12, v13
	v_add_f32_e32 v2, v14, v2
	v_add_f32_e32 v2, v15, v2
	v_add_f32_e32 v2, v16, v2
	v_add_f32_e32 v2, v17, v2
	v_add_f32_e32 v2, v10, v2
	v_add_f32_e32 v2, v11, v2
	s_waitcnt lgkmcnt(0)
	s_nop 1
	v_add_f32_dpp v2, v2, v2 quad_perm:[1,0,3,2] row_mask:0xf bank_mask:0xf
	s_nop 1
	v_add_f32_dpp v2, v2, v2 quad_perm:[2,3,0,1] row_mask:0xf bank_mask:0xf
	s_nop 1
	v_add_f32_dpp v2, v2, v2 row_half_mirror row_mask:0xf bank_mask:0xf
	s_nop 1
	v_add_f32_dpp v2, v2, v2 row_mirror row_mask:0xf bank_mask:0xf
	v_add_f32_e32 v2, 0x358637bd, v2
	v_cmp_gt_f32_e32 vcc, s10, v2
	v_mul_f32_e32 v10, 0x4b800000, v2
	s_nop 0
	v_cndmask_b32_e32 v2, v2, v10, vcc
	v_rsq_f32_e32 v2, v2
	s_nop 0
	v_mul_f32_e32 v10, 0x45800000, v2
	v_cndmask_b32_e32 v2, v2, v10, vcc
	v_mul_f32_e32 v2, 0x3db504f3, v2
	v_pk_mul_f32 v[10:11], v[4:5], v[2:3] op_sel_hi:[1,0]
	v_pk_mul_f32 v[12:13], v[6:7], v[2:3] op_sel_hi:[1,0]
	v_pk_mul_f32 v[8:9], v[8:9], v[2:3] op_sel_hi:[1,0]
	v_pk_mul_f32 v[0:1], v[0:1], v[2:3] op_sel_hi:[1,0]
	v_mul_lo_u32 v2, v27, s2
	v_cvt_pk_bf16_f32 v4, v10, v11
	v_cvt_pk_bf16_f32 v5, v12, v13
	v_cvt_pk_bf16_f32 v6, v8, v9
	v_cvt_pk_bf16_f32 v7, v0, v1
	v_add_u32_e32 v142, v141, v2
	ds_write_b128 v142, v[4:7]
	v_lshl_add_u32 v141, v27, 2, v35
	ds_read_b32 v2, v141
	v_and_b32_e32 v4, 0xfffffe00, v29
	v_bfe_u32 v5, v29, 4, 5
	v_or3_b32 v4, v5, v4, v143
	v_ashrrev_i32_e32 v5, 31, v4
	s_waitcnt lgkmcnt(0)
	v_pk_mul_f32 v[6:7], v[2:3], v[10:11] op_sel_hi:[0,1]
	v_pk_mul_f32 v[10:11], v[2:3], v[12:13] op_sel_hi:[0,1]
	v_pk_mul_f32 v[8:9], v[2:3], v[8:9] op_sel_hi:[0,1]
	v_lshl_add_u64 v[4:5], v[4:5], 4, v[20:21]
	v_cvt_pk_bf16_f32 v6, v6, v7
	v_cvt_pk_bf16_f32 v7, v10, v11
	v_cvt_pk_bf16_f32 v8, v8, v9
	v_pk_mul_f32 v[0:1], v[2:3], v[0:1] op_sel_hi:[0,1]
	v_cvt_pk_bf16_f32 v9, v0, v1
	global_store_dwordx2 v[4:5], v[6:7], off
	global_store_dwordx2 v[4:5], v[8:9], off offset:512
	ds_read_b128 v[12:15], v26 offset:512
	ds_read_b128 v[16:19], v26 offset:528
	v_lshlrev_b32_e32 v0, 16, v50
	v_lshlrev_b32_e32 v4, 16, v48
	v_and_b32_e32 v2, 0xffff0000, v50
	s_waitcnt lgkmcnt(1)
	v_fma_f32 v4, v12, v4, 0
	s_waitcnt lgkmcnt(0)
	v_mul_f32_e32 v5, v16, v0
	v_and_b32_e32 v1, 0xffff0000, v48
	v_cndmask_b32_e64 v0, 0, v4, s[40:41]
	v_cndmask_b32_e64 v4, 0, v5, s[40:41]
	v_mul_f32_e32 v5, v17, v2
	v_fma_f32 v1, v13, v1, 0
	v_cndmask_b32_e64 v5, 0, v5, s[40:41]
	v_add_f32_e32 v4, 0, v4
	v_cndmask_b32_e64 v1, 0, v1, s[40:41]
	v_mov_b32_e32 v2, v3
	v_mov_b32_e32 v6, v3
	v_mov_b32_e32 v7, v3
	v_add_f32_e32 v5, 0, v5
	s_and_saveexec_b64 s[2:3], s[30:31]
	s_xor_b64 s[2:3], exec, s[2:3]
	s_or_saveexec_b64 s[2:3], s[2:3]
	v_mov_b32_e32 v8, 0
	s_xor_b64 exec, exec, s[2:3]
	v_lshlrev_b32_e32 v8, 16, v51
	v_lshlrev_b32_e32 v2, 16, v49
	v_fma_f32 v2, v14, v2, 0
	v_mul_f32_e32 v8, v18, v8
	s_or_b64 exec, exec, s[2:3]
	v_add_f32_e32 v12, v6, v8
	v_mov_b64_e32 v[10:11], v[6:7]
	v_mov_b64_e32 v[8:9], v[4:5]
	v_mov_b64_e32 v[6:7], v[2:3]
	v_mov_b64_e32 v[4:5], v[0:1]
	v_mov_b32_e32 v10, v12
	s_and_saveexec_b64 s[2:3], s[30:31]
	s_xor_b64 s[2:3], exec, s[2:3]
	v_add_f32_e32 v7, 0, v3
	s_or_saveexec_b64 s[2:3], s[2:3]
	v_mov_b32_e32 v0, 0
	s_xor_b64 exec, exec, s[2:3]
	v_and_b32_e32 v0, 0xffff0000, v49
	v_and_b32_e32 v1, 0xffff0000, v51
	v_mov_b32_e32 v7, v3
	v_fmac_f32_e32 v7, v15, v0
	v_mul_f32_e32 v0, v19, v1
	s_or_b64 exec, exec, s[2:3]
	ds_read_b128 v[12:15], v26 offset:2048
	ds_read_b128 v[16:19], v26 offset:2064
	v_add_f32_e32 v11, v11, v0
	s_and_saveexec_b64 s[2:3], s[24:25]
	s_xor_b64 s[2:3], exec, s[2:3]
	v_add_f32_e32 v4, 0, v4
	s_or_saveexec_b64 s[2:3], s[2:3]
	v_mov_b32_e32 v0, 0
	s_xor_b64 exec, exec, s[2:3]
	s_cbranch_execz .LBB0_548
	v_lshlrev_b32_e32 v0, 16, v58
	v_lshlrev_b32_e32 v1, 16, v56
	s_waitcnt lgkmcnt(1)
	v_fmac_f32_e32 v4, v12, v1
	s_waitcnt lgkmcnt(0)
	v_mul_f32_e32 v0, v16, v0

; #define LAS __attribute__((address_space(3)))
; DI unsigned pk2(float lo, float hi) { f32x2 v = {lo, hi}; bf2_t b = __builtin_convertvector(v, bf2_t); return __builtin_bit_cast(unsigned, b); }
; DI bf16_t f2bf(float f) { return (bf16_t)(pk2(f, 0.f) & 0xffffu); }
; DI u32x4 pack8(const float* f) { u32x4 w; w.x = pk2(f[0], f[1]); w.y = pk2(f[2], f[3]); w.z = pk2(f[4], f[5]); w.w = pk2(f[6], f[7]); return w; }
; DI void gdn_intra(LAS unsigned char* lds, PP p, int l, int first, int stride) {
;     ...
;             for (int i = 0; i < 8; ++i) a[i] = a[i] / (1.f + __expf(-a[i]));
;             if (mat < 2) {
;                 float ss = 0.f;
; #pragma unroll
;                 for (int i = 0; i < 8; ++i) ss += a[i] * a[i];
;                 ss += __shfl_xor(ss, 1); ss += __shfl_xor(ss, 2); ss += __shfl_xor(ss, 4); ss += __shfl_xor(ss, 8);
;                 const float sc = rsqrtf(ss + 1e-6f) * (mat == 0 ? 0.08838834764831845f : 1.f);
; #pragma unroll
;                 for (int i = 0; i < 8; ++i) a[i] *= sc;
;             }
;             if (mat == 0) {
;                 *(LAS u32x4*)(Qn + j * 136 + o * 8) = pack8(a);
;                 const float eg = sce[j]; const int ct = j >> 5, s = o >> 1, part = o & 1;
;                 unsigned char* q0 = fb + 16384 + ((size_t)((ct * 8 + s) * 64 + (j & 31))) * 16 + 8 * part;
;                 u32x2 lo, hi2; lo.x = pk2(a[0] * eg, a[1] * eg); lo.y = pk2(a[2] * eg, a[3] * eg); hi2.x = pk2(a[4] * eg, a[5] * eg); hi2.y = pk2(a[6] * eg, a[7] * eg);
;                 *(u32x2*)q0 = lo; *(u32x2*)(q0 + 32 * 16) = hi2;
;             } else if (mat == 1) {
;                 *(LAS u32x4*)(Kn + j * 136 + o * 8) = pack8(a);
;                 const float f1 = scb[j] * sce[j], f2 = scl[j];
; #pragma unroll
;                 for (int i = 0; i < 8; ++i) { XTk[xsw(o * 8 + i, j)] = f2bf(a[i] * f1); KT2[xsw(o * 8 + i, j)] = f2bf(a[i] * f2); }
.LBB0_592:
	s_or_b64 exec, exec, s[2:3]
	v_add_f32_e32 v2, v0, v11
	v_mul_f32_e32 v0, 0xbfb8aa3b, v2
	v_exp_f32_e32 v1, v0
	v_mul_f32_e32 v0, 0xbfb8aa3b, v4
	s_waitcnt lgkmcnt(1)
	v_exp_f32_e32 v12, v0
	v_mul_f32_e32 v0, 0xbfb8aa3b, v5
	v_exp_f32_e32 v13, v0
	v_mul_f32_e32 v0, 0xbfb8aa3b, v6
	v_exp_f32_e32 v14, v0
	v_mul_f32_e32 v0, 0xbfb8aa3b, v7
	v_exp_f32_e32 v15, v0
	v_mul_f32_e32 v0, 0xbfb8aa3b, v8
	s_waitcnt lgkmcnt(0)
	v_exp_f32_e32 v16, v0
	v_mul_f32_e32 v0, 0xbfb8aa3b, v9
	v_exp_f32_e32 v17, v0
	v_mul_f32_e32 v0, 0xbfb8aa3b, v10
	v_exp_f32_e32 v0, v0
	v_pk_add_f32 v[14:15], v[14:15], 1.0 op_sel_hi:[1,0]
	v_pk_add_f32 v[16:17], v[16:17], 1.0 op_sel_hi:[1,0]
	v_pk_add_f32 v[12:13], v[12:13], 1.0 op_sel_hi:[1,0]
	v_pk_add_f32 v[0:1], v[0:1], 1.0 op_sel_hi:[1,0]
	v_lshlrev_b32_e32 v143, 3, v28
	v_rcp_f32_e32 v18, v1
	s_nop 0
	v_mul_u32_u24_e32 v144, 0x240, v28
	v_add_u32_e32 v20, 0x11800, v132
	v_mul_f32_e32 v21, v2, v18
	v_fma_f32 v35, -v1, v21, v2
	v_fmac_f32_e32 v21, v35, v18
	v_div_fixup_f32 v1, v21, v1, v2
	v_rcp_f32_e32 v11, v0
	s_nop 0
	v_mul_f32_e32 v19, v10, v11
	v_fma_f32 v21, -v0, v19, v10
	v_fmac_f32_e32 v19, v21, v11
	v_div_fixup_f32 v0, v19, v0, v10
	v_rcp_f32_e32 v18, v17
	s_nop 0
	v_pk_mul_f32 v[10:11], v[0:1], v[0:1]
	v_mul_f32_e32 v21, v9, v18
	v_fma_f32 v35, -v17, v21, v9
	v_fmac_f32_e32 v21, v35, v18
	v_div_fixup_f32 v9, v21, v17, v9
	v_rcp_f32_e32 v17, v16
	s_nop 0
	v_mul_f32_e32 v19, v8, v17
	v_fma_f32 v21, -v16, v19, v8
	v_fmac_f32_e32 v19, v21, v17
	v_div_fixup_f32 v8, v19, v16, v8
	v_rcp_f32_e32 v18, v15
	s_nop 0
	v_pk_mul_f32 v[16:17], v[8:9], v[8:9]
	v_mul_f32_e32 v21, v7, v18
	v_fma_f32 v35, -v15, v21, v7
	v_fmac_f32_e32 v21, v35, v18
	v_div_fixup_f32 v7, v21, v15, v7
	v_rcp_f32_e32 v15, v14
	s_nop 0
	v_mul_f32_e32 v19, v6, v15
	v_fma_f32 v21, -v14, v19, v6
	v_fmac_f32_e32 v19, v21, v15
	v_div_fixup_f32 v6, v19, v14, v6
	v_rcp_f32_e32 v18, v13
	s_nop 0
	v_pk_mul_f32 v[14:15], v[6:7], v[6:7]
	v_mul_f32_e32 v21, v5, v18
	v_fma_f32 v35, -v13, v21, v5
	v_fmac_f32_e32 v21, v35, v18
	v_div_fixup_f32 v5, v21, v13, v5
	v_rcp_f32_e32 v13, v12
	s_nop 0
	s_movk_i32 s2, 0x240
	v_mad_u32_u24 v151, v28, s2, v227
	v_mul_f32_e32 v19, v4, v13
	v_fma_f32 v21, -v12, v19, v4
	v_fmac_f32_e32 v19, v21, v13
	v_div_fixup_f32 v4, v19, v12, v4
	v_pk_mul_f32 v[12:13], v[4:5], v[4:5]
	s_nop 0
	v_add_f32_e32 v2, v12, v13
	v_add_f32_e32 v2, v14, v2
	v_add_f32_e32 v2, v15, v2
	v_add_f32_e32 v2, v16, v2
	v_add_f32_e32 v2, v17, v2
	v_add_f32_e32 v2, v10, v2
	v_add_f32_e32 v2, v11, v2
	s_waitcnt lgkmcnt(0)
	s_nop 1
	v_add_f32_dpp v2, v2, v2 quad_perm:[1,0,3,2] row_mask:0xf bank_mask:0xf
	s_nop 1
	v_add_f32_dpp v2, v2, v2 quad_perm:[2,3,0,1] row_mask:0xf bank_mask:0xf
	s_nop 1
	v_add_f32_dpp v2, v2, v2 row_half_mirror row_mask:0xf bank_mask:0xf
	s_nop 1
	v_add_f32_dpp v2, v2, v2 row_mirror row_mask:0xf bank_mask:0xf
	v_add_f32_e32 v2, 0x358637bd, v2
	v_cmp_gt_f32_e32 vcc, s10, v2
	v_mul_f32_e32 v10, 0x4b800000, v2
	s_nop 0
	v_cndmask_b32_e32 v2, v2, v10, vcc
	v_rsq_f32_e32 v2, v2
	s_nop 0
	v_mul_f32_e32 v10, 0x45800000, v2
	v_cndmask_b32_e32 v2, v2, v10, vcc
	v_pk_mul_f32 v[10:11], v[4:5], v[2:3] op_sel_hi:[1,0]
	v_pk_mul_f32 v[12:13], v[6:7], v[2:3] op_sel_hi:[1,0]
	v_pk_mul_f32 v[8:9], v[8:9], v[2:3] op_sel_hi:[1,0]
	v_pk_mul_f32 v[0:1], v[0:1], v[2:3] op_sel_hi:[1,0]
	v_cvt_pk_bf16_f32 v4, v10, v11
	v_cvt_pk_bf16_f32 v5, v12, v13
	v_cvt_pk_bf16_f32 v6, v8, v9
	v_cvt_pk_bf16_f32 v7, v0, v1
	v_lshlrev_b32_e32 v2, 2, v24
	ds_write_b128 v140, v[4:7] offset:17408
	v_add_u32_e32 v35, v23, v2
	ds_read_b32 v4, v35
	ds_read_b32 v5, v139
	v_add_u32_e32 v2, v30, v2
	ds_read_b32 v2, v2
	v_bitop3_b32 v139, v143, 56, v24 bitop3:0x48
	v_bfe_u32 v140, v138, 4, 3
	s_waitcnt lgkmcnt(1)
	v_mul_f32_e32 v4, v4, v5
	v_or_b32_e32 v5, v139, v140
	v_or_b32_e32 v7, v5, v144
	v_mul_f32_e32 v6, v4, v10
	v_lshlrev_b32_e32 v7, 1, v7
	v_cvt_pk_bf16_f32 v6, v6, s0
	v_add_u32_e32 v14, v132, v7
	ds_write_b16 v14, v6 offset:34816
	s_waitcnt lgkmcnt(1)
; #define LAS __attribute__((address_space(3)))
; DI bf16_t f2bf(float f) { return (bf16_t)(pk2(f, 0.f) & 0xffffu); }
; DI void unpack8(u32x4 w, float* f) { f[0] = bflo(w.x); f[1] = bfhi(w.x); f[2] = bflo(w.y); f[3] = bfhi(w.y); f[4] = bflo(w.z); f[5] = bfhi(w.z); f[6] = bflo(w.w); f[7] = bfhi(w.w); }
; DI u32x4 pack8(const float* f) { u32x4 w; w.x = pk2(f[0], f[1]); w.y = pk2(f[2], f[3]); w.z = pk2(f[4], f[5]); w.w = pk2(f[6], f[7]); return w; }
; DI void gdn_intra(LAS unsigned char* lds, PP p, int l, int first, int stride) {
;     ...
;             for (int kk = 0; kk < 4; ++kk) { const bool ok = tok0 + j - 3 + kk >= 0;
;                 float x[8]; unpack8(R[(mat * 2 + it) * 4 + kk], x);
;                 const f32x4 w0 = *(const LAS f32x4*)(CW + kk * 384 + mat * 128 + o * 8), w1 = *(const LAS f32x4*)(CW + kk * 384 + mat * 128 + o * 8 + 4);
;                 for (int i = 0; i < 4; ++i) { a[i] += ok ? w0[i] * x[i] : 0.f; a[4 + i] += ok ? w1[i] * x[4 + i] : 0.f; } }
;     ...
;                 *(LAS u32x4*)(Kn + j * 136 + o * 8) = pack8(a);
;                 const float f1 = scb[j] * sce[j], f2 = scl[j];
; #pragma unroll
;                 for (int i = 0; i < 8; ++i) { XTk[xsw(o * 8 + i, j)] = f2bf(a[i] * f1); KT2[xsw(o * 8 + i, j)] = f2bf(a[i] * f2); }
	v_mul_f32_e32 v6, v2, v10
	v_cvt_pk_bf16_f32 v6, v6, s0
	v_add_u32_e32 v7, v20, v7
	ds_write_b16 v7, v6
	v_mul_f32_e32 v6, v4, v11
	v_mov_b32_e32 v7, 0x48
	v_cvt_pk_bf16_f32 v6, v6, s0
	v_mad_u32_u24 v145, v28, s2, v7
	v_add_u32_e32 v7, v5, v145
	ds_write_b16 v14, v6 offset:34960
	v_mul_f32_e32 v6, v2, v11
	v_cvt_pk_bf16_f32 v6, v6, s0
	v_lshl_add_u32 v7, v7, 1, v20
	ds_write_b16 v7, v6
	v_mul_f32_e32 v6, v4, v12
	v_mov_b32_e32 v7, 0x90
	v_cvt_pk_bf16_f32 v6, v6, s0
	v_mad_u32_u24 v146, v28, s2, v7
	v_add_u32_e32 v7, v5, v146
	ds_write_b16 v14, v6 offset:35104
	v_mul_f32_e32 v6, v2, v12
	v_cvt_pk_bf16_f32 v6, v6, s0
	v_lshl_add_u32 v7, v7, 1, v20
	ds_write_b16 v7, v6
	v_mul_f32_e32 v6, v4, v13
	v_mov_b32_e32 v7, 0xd8
	v_cvt_pk_bf16_f32 v6, v6, s0
	v_mad_u32_u24 v147, v28, s2, v7
	v_add_u32_e32 v7, v5, v147
	ds_write_b16 v14, v6 offset:35248
	v_mul_f32_e32 v6, v2, v13
	v_cvt_pk_bf16_f32 v6, v6, s0
	v_lshl_add_u32 v7, v7, 1, v20
	ds_write_b16 v7, v6
	v_mul_f32_e32 v6, v4, v8
	v_mov_b32_e32 v7, 0x120
	v_cvt_pk_bf16_f32 v6, v6, s0
	v_mad_u32_u24 v148, v28, s2, v7
	v_add_u32_e32 v7, v5, v148
	ds_write_b16 v14, v6 offset:35392
	v_mul_f32_e32 v6, v2, v8
	v_cvt_pk_bf16_f32 v6, v6, s0
	v_lshl_add_u32 v7, v7, 1, v20
	ds_write_b16 v7, v6
	v_mul_f32_e32 v6, v4, v9
	v_mov_b32_e32 v7, 0x168
	v_cvt_pk_bf16_f32 v6, v6, s0
	v_mad_u32_u24 v149, v28, s2, v7
	v_add_u32_e32 v7, v5, v149
	ds_write_b16 v14, v6 offset:35536
	v_mul_f32_e32 v6, v2, v9
	v_cvt_pk_bf16_f32 v6, v6, s0
	v_lshl_add_u32 v7, v7, 1, v20
	ds_write_b16 v7, v6
	v_mov_b32_e32 v7, 0x1b0
	v_mul_f32_e32 v6, v4, v0
	v_mad_u32_u24 v150, v28, s2, v7
	v_cvt_pk_bf16_f32 v6, v6, s0
	v_add_u32_e32 v7, v5, v150
	v_mul_f32_e32 v0, v2, v0
	ds_write_b16 v14, v6 offset:35680
	v_cvt_pk_bf16_f32 v0, v0, s0
	v_lshl_add_u32 v6, v7, 1, v20
	ds_write_b16 v6, v0
	v_mul_f32_e32 v0, v4, v1
	v_cvt_pk_bf16_f32 v0, v0, s0
	v_add_u32_e32 v4, v5, v151
	ds_write_b16 v14, v0 offset:35824
	v_mul_f32_e32 v0, v2, v1
	v_cvt_pk_bf16_f32 v0, v0, s0
	v_lshl_add_u32 v1, v4, 1, v20
	ds_write_b16 v1, v0
	ds_read_b128 v[12:15], v26 offset:512
	ds_read_b128 v[16:19], v26 offset:528
	v_lshlrev_b32_e32 v0, 16, v82
	v_lshlrev_b32_e32 v4, 16, v80
	v_and_b32_e32 v2, 0xffff0000, v82
	s_waitcnt lgkmcnt(1)
	v_fma_f32 v4, v12, v4, 0
	s_waitcnt lgkmcnt(0)
	v_mul_f32_e32 v5, v16, v0
	v_and_b32_e32 v1, 0xffff0000, v80
	v_cndmask_b32_e64 v0, 0, v4, s[44:45]
	v_cndmask_b32_e64 v4, 0, v5, s[44:45]
	v_mul_f32_e32 v5, v17, v2
	v_fma_f32 v1, v13, v1, 0
	v_cndmask_b32_e64 v5, 0, v5, s[44:45]
	v_add_f32_e32 v4, 0, v4
	v_cndmask_b32_e64 v1, 0, v1, s[44:45]
	v_mov_b32_e32 v2, v3
	v_mov_b32_e32 v6, v3
	v_mov_b32_e32 v7, v3
	v_add_f32_e32 v5, 0, v5
	s_and_saveexec_b64 s[2:3], s[42:43]
	s_xor_b64 s[2:3], exec, s[2:3]
	s_or_saveexec_b64 s[2:3], s[2:3]
	v_mov_b32_e32 v8, 0
	s_xor_b64 exec, exec, s[2:3]
	v_lshlrev_b32_e32 v8, 16, v83
	v_lshlrev_b32_e32 v2, 16, v81
	v_fma_f32 v2, v14, v2, 0
	v_mul_f32_e32 v8, v18, v8
	s_or_b64 exec, exec, s[2:3]
	v_add_f32_e32 v12, v6, v8
	v_mov_b64_e32 v[10:11], v[6:7]
	v_mov_b64_e32 v[8:9], v[4:5]
	v_mov_b64_e32 v[6:7], v[2:3]
	v_mov_b64_e32 v[4:5], v[0:1]
	v_mov_b32_e32 v10, v12
	s_and_saveexec_b64 s[2:3], s[42:43]
	s_xor_b64 s[2:3], exec, s[2:3]
	v_add_f32_e32 v7, 0, v3
	s_or_saveexec_b64 s[2:3], s[2:3]
	v_mov_b32_e32 v0, 0
	s_xor_b64 exec, exec, s[2:3]
	v_and_b32_e32 v0, 0xffff0000, v81
	v_and_b32_e32 v1, 0xffff0000, v83
	v_mov_b32_e32 v7, v3
	v_fmac_f32_e32 v7, v15, v0
	v_mul_f32_e32 v0, v19, v1
	s_or_b64 exec, exec, s[2:3]
	ds_read_b128 v[12:15], v26 offset:2048
	ds_read_b128 v[16:19], v26 offset:2064
	v_add_f32_e32 v11, v11, v0
	s_and_saveexec_b64 s[2:3], s[34:35]
	s_xor_b64 s[2:3], exec, s[2:3]
	v_add_f32_e32 v4, 0, v4
	s_or_saveexec_b64 s[2:3], s[2:3]
	v_mov_b32_e32 v0, 0
	s_xor_b64 exec, exec, s[2:3]
	s_cbranch_execz .LBB0_602
	v_lshlrev_b32_e32 v0, 16, v90
	v_lshlrev_b32_e32 v1, 16, v88
	s_waitcnt lgkmcnt(1)
	v_fmac_f32_e32 v4, v12, v1
	s_waitcnt lgkmcnt(0)
	v_mul_f32_e32 v0, v16, v0
